# A1+E1+E2: sk_final partial loads batched (2 round trips instead of 36); conv kscale loads batched (1 wait instead of 16) at 7 sites
# speedup vs baseline: 1.0043x; 1.0043x over previous
; #define LAS __attribute__((address_space(3)))
; __device__ __forceinline__ void transpose_item(const float* W, int ldw, int sc0, int k0, const float* kscale, bf16_t* WT, int Kd, int dr0, int nvalid, LAS float* scr, int lane) {
;     const int l16 = lane & 15, kq = lane >> 4;
;     f32x4 v[16];
; #pragma unroll
;     for (int i = 0; i < 16; ++i) { const int kk = 4 * i + kq; v[i] = (f32x4){0.f, 0.f, 0.f, 0.f};
;         if (4 * l16 < nvalid) v[i] = __builtin_nontemporal_load((const f32x4*)(W + (size_t)(k0 + kk) * ldw + sc0 + 4 * l16)); }
;     if (kscale) {
; #pragma unroll
;         for (int i = 0; i < 16; ++i) v[i] = v[i] * kscale[k0 + 4 * i + kq]; }
; __device__ __forceinline__ void conv_item(CArgs* a, int l, int r, LAS float* scr, int lane) {
;     ...
;     if (r < IT_UP) { const int kb = r / 128, nb = r - kb * 128;
;         transpose_item(a->in[28] + (size_t)l * D * DFF, DFF, 64 * nb, 64 * kb, a->in[8] + l * D, (bf16_t*)(lw + LW_UP), D, 64 * nb, 64, scr, lane); return; }
.LBB0_21:
	s_andn2_saveexec_b64 s[6:7], s[24:25]
	s_cbranch_execz .LBB0_25
	s_load_dwordx2 s[26:27], s[12:13], 0xe0
	s_load_dwordx2 s[24:25], s[12:13], 0x40
	v_add_u32_e32 v4, 0xffffd5e0, v125
	v_add_u32_e32 v3, 0xfff57800, v101
	v_and_b32_e32 v3, 0x1fc0, v3
	v_lshrrev_b32_e32 v4, 1, v4
	v_and_b32_e32 v90, 0x7fffffc0, v4
	v_lshlrev_b32_e32 v4, 2, v3
	v_mov_b32_e32 v5, v2
	v_or_b32_e32 v68, v90, v71
	s_waitcnt lgkmcnt(0)
	v_lshl_add_u64 v[4:5], s[26:27], 0, v[4:5]
	v_lshlrev_b32_e32 v6, 2, v78
	v_mov_b32_e32 v7, v2
	v_lshl_add_u64 v[60:61], v[4:5], 0, v[6:7]
	v_mov_b32_e32 v69, v2
	v_or_b32_e32 v6, 4, v68
	v_or_b32_e32 v12, 8, v68
	v_mov_b32_e32 v13, v2
	v_or_b32_e32 v14, 12, v68
	v_mov_b32_e32 v15, v2
	v_or_b32_e32 v20, 16, v68
	v_mov_b32_e32 v21, v2
	v_or_b32_e32 v22, 20, v68
	v_mov_b32_e32 v23, v2
	v_or_b32_e32 v28, 24, v68
	v_mov_b32_e32 v29, v2
	v_or_b32_e32 v30, 28, v68
	v_mov_b32_e32 v31, v2
	v_or_b32_e32 v36, 32, v68
	v_mov_b32_e32 v37, v2
	v_or_b32_e32 v38, 36, v68
	v_mov_b32_e32 v39, v2
	v_or_b32_e32 v44, 40, v68
	v_mov_b32_e32 v45, v2
	v_or_b32_e32 v46, 44, v68
	v_mov_b32_e32 v47, v2
	v_or_b32_e32 v52, 48, v68
	v_mov_b32_e32 v53, v2
	v_or_b32_e32 v54, 52, v68
	v_mov_b32_e32 v55, v2
	v_or_b32_e32 v62, 56, v68
	v_mov_b32_e32 v63, v2
	v_or_b32_e32 v64, 60, v68
	v_mov_b32_e32 v65, v2
	v_lshlrev_b64 v[4:5], 15, v[68:69]
	v_lshlrev_b64 v[6:7], 15, v[6:7]
	v_lshlrev_b64 v[12:13], 15, v[12:13]
	v_lshlrev_b64 v[14:15], 15, v[14:15]
	v_lshlrev_b64 v[20:21], 15, v[20:21]
	v_lshlrev_b64 v[22:23], 15, v[22:23]
	v_lshlrev_b64 v[28:29], 15, v[28:29]
	v_lshlrev_b64 v[30:31], 15, v[30:31]
	v_lshlrev_b64 v[36:37], 15, v[36:37]
	v_lshlrev_b64 v[38:39], 15, v[38:39]
	v_lshlrev_b64 v[44:45], 15, v[44:45]
	v_lshlrev_b64 v[46:47], 15, v[46:47]
	v_lshlrev_b64 v[52:53], 15, v[52:53]
	v_lshlrev_b64 v[54:55], 15, v[54:55]
	v_lshlrev_b64 v[62:63], 15, v[62:63]
	v_lshlrev_b64 v[64:65], 15, v[64:65]
	v_lshl_add_u64 v[4:5], v[60:61], 0, v[4:5]
	v_lshl_add_u64 v[6:7], v[60:61], 0, v[6:7]
	v_lshl_add_u64 v[12:13], v[60:61], 0, v[12:13]
	v_lshl_add_u64 v[14:15], v[60:61], 0, v[14:15]
	v_lshl_add_u64 v[20:21], v[60:61], 0, v[20:21]
	v_lshl_add_u64 v[22:23], v[60:61], 0, v[22:23]
	v_lshl_add_u64 v[28:29], v[60:61], 0, v[28:29]
	v_lshl_add_u64 v[30:31], v[60:61], 0, v[30:31]
	v_lshl_add_u64 v[36:37], v[60:61], 0, v[36:37]
	v_lshl_add_u64 v[38:39], v[60:61], 0, v[38:39]
	v_lshl_add_u64 v[44:45], v[60:61], 0, v[44:45]
	v_lshl_add_u64 v[46:47], v[60:61], 0, v[46:47]
	v_lshl_add_u64 v[52:53], v[60:61], 0, v[52:53]
	v_lshl_add_u64 v[54:55], v[60:61], 0, v[54:55]
	v_lshl_add_u64 v[62:63], v[60:61], 0, v[62:63]
	v_lshl_add_u64 v[60:61], v[60:61], 0, v[64:65]
	global_load_dwordx4 v[8:11], v[4:5], off nt
	s_nop 0
	global_load_dwordx4 v[4:7], v[6:7], off nt
	s_nop 0
	global_load_dwordx4 v[16:19], v[12:13], off nt
	s_nop 0
	global_load_dwordx4 v[12:15], v[14:15], off nt
	s_nop 0
	global_load_dwordx4 v[24:27], v[20:21], off nt
	s_nop 0
	global_load_dwordx4 v[20:23], v[22:23], off nt
	s_nop 0
	global_load_dwordx4 v[32:35], v[28:29], off nt
	s_nop 0
	global_load_dwordx4 v[28:31], v[30:31], off nt
	s_nop 0
	global_load_dwordx4 v[40:43], v[36:37], off nt
	s_nop 0
	global_load_dwordx4 v[36:39], v[38:39], off nt
	s_nop 0
	global_load_dwordx4 v[48:51], v[44:45], off nt
	s_nop 0
	global_load_dwordx4 v[44:47], v[46:47], off nt
	s_nop 0
	global_load_dwordx4 v[56:59], v[52:53], off nt
	s_nop 0
	global_load_dwordx4 v[52:55], v[54:55], off nt
	s_nop 0
	global_load_dwordx4 v[64:67], v[62:63], off nt
	s_nop 0
	global_load_dwordx4 v[60:63], v[60:61], off nt
	s_cmp_eq_u64 s[24:25], 0
	s_cbranch_scc1 .LBB0_24
	v_lshl_add_u64 v[68:69], v[68:69], 2, s[24:25]
	global_load_dword v160, v[68:69], off
	global_load_dword v161, v[68:69], off offset:16
	global_load_dword v162, v[68:69], off offset:32
	global_load_dword v163, v[68:69], off offset:48
	global_load_dword v164, v[68:69], off offset:64
	global_load_dword v165, v[68:69], off offset:80
	global_load_dword v166, v[68:69], off offset:96
	global_load_dword v167, v[68:69], off offset:112
	global_load_dword v168, v[68:69], off offset:128
	global_load_dword v169, v[68:69], off offset:144
	global_load_dword v170, v[68:69], off offset:160
	global_load_dword v171, v[68:69], off offset:176
	global_load_dword v172, v[68:69], off offset:192
	global_load_dword v173, v[68:69], off offset:208
	global_load_dword v174, v[68:69], off offset:224
	global_load_dword v175, v[68:69], off offset:240
	s_waitcnt vmcnt(0)
	v_pk_mul_f32 v[10:11], v[10:11], v[160:161] op_sel_hi:[1,0]
	v_pk_mul_f32 v[8:9], v[8:9], v[160:161] op_sel_hi:[1,0]
	v_pk_mul_f32 v[6:7], v[6:7], v[160:161] op_sel:[0,1]
	v_pk_mul_f32 v[4:5], v[4:5], v[160:161] op_sel:[0,1]
	v_pk_mul_f32 v[18:19], v[18:19], v[162:163] op_sel_hi:[1,0]
	v_pk_mul_f32 v[16:17], v[16:17], v[162:163] op_sel_hi:[1,0]
	v_pk_mul_f32 v[14:15], v[14:15], v[162:163] op_sel:[0,1]
	v_pk_mul_f32 v[12:13], v[12:13], v[162:163] op_sel:[0,1]
	v_pk_mul_f32 v[26:27], v[26:27], v[164:165] op_sel_hi:[1,0]
	v_pk_mul_f32 v[24:25], v[24:25], v[164:165] op_sel_hi:[1,0]
	v_pk_mul_f32 v[22:23], v[22:23], v[164:165] op_sel:[0,1]
	v_pk_mul_f32 v[20:21], v[20:21], v[164:165] op_sel:[0,1]
	v_pk_mul_f32 v[34:35], v[34:35], v[166:167] op_sel_hi:[1,0]
	v_pk_mul_f32 v[32:33], v[32:33], v[166:167] op_sel_hi:[1,0]
	v_pk_mul_f32 v[30:31], v[30:31], v[166:167] op_sel:[0,1]
	v_pk_mul_f32 v[28:29], v[28:29], v[166:167] op_sel:[0,1]
	v_pk_mul_f32 v[42:43], v[42:43], v[168:169] op_sel_hi:[1,0]
	v_pk_mul_f32 v[40:41], v[40:41], v[168:169] op_sel_hi:[1,0]
	v_pk_mul_f32 v[38:39], v[38:39], v[168:169] op_sel:[0,1]
	v_pk_mul_f32 v[36:37], v[36:37], v[168:169] op_sel:[0,1]
	v_pk_mul_f32 v[50:51], v[50:51], v[170:171] op_sel_hi:[1,0]
	v_pk_mul_f32 v[48:49], v[48:49], v[170:171] op_sel_hi:[1,0]
	v_pk_mul_f32 v[46:47], v[46:47], v[170:171] op_sel:[0,1]
	v_pk_mul_f32 v[44:45], v[44:45], v[170:171] op_sel:[0,1]
	v_pk_mul_f32 v[58:59], v[58:59], v[172:173] op_sel_hi:[1,0]
	v_pk_mul_f32 v[56:57], v[56:57], v[172:173] op_sel_hi:[1,0]
	v_pk_mul_f32 v[54:55], v[54:55], v[172:173] op_sel:[0,1]
	v_pk_mul_f32 v[52:53], v[52:53], v[172:173] op_sel:[0,1]
	v_pk_mul_f32 v[66:67], v[66:67], v[174:175] op_sel_hi:[1,0]
	v_pk_mul_f32 v[64:65], v[64:65], v[174:175] op_sel_hi:[1,0]
	v_pk_mul_f32 v[62:63], v[62:63], v[174:175] op_sel:[0,1]
	v_pk_mul_f32 v[60:61], v[60:61], v[174:175] op_sel:[0,1]

; #define LAS __attribute__((address_space(3)))
; __device__ __forceinline__ void transpose_item(const float* W, int ldw, int sc0, int k0, const float* kscale, bf16_t* WT, int Kd, int dr0, int nvalid, LAS float* scr, int lane) {
;     const int l16 = lane & 15, kq = lane >> 4;
;     f32x4 v[16];
; #pragma unroll
;     for (int i = 0; i < 16; ++i) { const int kk = 4 * i + kq; v[i] = (f32x4){0.f, 0.f, 0.f, 0.f};
;         if (4 * l16 < nvalid) v[i] = __builtin_nontemporal_load((const f32x4*)(W + (size_t)(k0 + kk) * ldw + sc0 + 4 * l16)); }
;     if (kscale) {
; #pragma unroll
;         for (int i = 0; i < 16; ++i) v[i] = v[i] * kscale[k0 + 4 * i + kq]; }
; __device__ __forceinline__ void conv_item(CArgs* a, int l, int r, LAS float* scr, int lane) {
;     ...
;     if (r < IT_UP) { const int kb = r / 128, nb = r - kb * 128;
;         transpose_item(a->in[28] + (size_t)l * D * DFF, DFF, 64 * nb, 64 * kb, a->in[8] + l * D, (bf16_t*)(lw + LW_UP), D, 64 * nb, 64, scr, lane); return; }
.LBB0_231:
	s_andn2_saveexec_b64 s[16:17], s[16:17]
	s_cbranch_execz .LBB0_235
	s_load_dwordx2 s[18:19], s[8:9], 0xe0
	v_add_u32_e32 v4, 0xffffd5e0, v3
	s_lshl_b64 s[20:21], s[80:81], 26
	v_lshlrev_b32_e32 v3, 6, v4
	v_lshrrev_b32_e32 v4, 1, v4
	s_waitcnt lgkmcnt(0)
	s_add_u32 s20, s18, s20
	v_and_b32_e32 v3, 0x1fc0, v3
	v_and_b32_e32 v72, 0x7fffffc0, v4
	v_lshrrev_b32_e32 v73, 4, v79
	s_addc_u32 s21, s19, s21
	v_and_b32_e32 v6, 15, v7
	v_or_b32_e32 v70, v72, v73
	v_lshlrev_b32_e32 v4, 2, v3
	v_mov_b32_e32 v5, v2
	v_lshl_add_u64 v[4:5], s[20:21], 0, v[4:5]
	v_lshlrev_b32_e32 v68, 4, v6
	v_mov_b32_e32 v69, v2
	v_mov_b32_e32 v71, v2
	v_or_b32_e32 v8, 4, v70
	v_mov_b32_e32 v9, v2
	v_or_b32_e32 v12, 8, v70
	v_mov_b32_e32 v13, v2
	v_or_b32_e32 v16, 12, v70
	v_mov_b32_e32 v17, v2
	v_or_b32_e32 v20, 16, v70
	v_mov_b32_e32 v21, v2
	v_or_b32_e32 v24, 20, v70
	v_mov_b32_e32 v25, v2
	v_or_b32_e32 v28, 24, v70
	v_mov_b32_e32 v29, v2
	v_or_b32_e32 v32, 28, v70
	v_mov_b32_e32 v33, v2
	v_or_b32_e32 v36, 32, v70
	v_mov_b32_e32 v37, v2
	v_or_b32_e32 v40, 36, v70
	v_mov_b32_e32 v41, v2
	v_or_b32_e32 v44, 40, v70
	v_mov_b32_e32 v45, v2
	v_or_b32_e32 v48, 44, v70
	v_mov_b32_e32 v49, v2
	v_or_b32_e32 v52, 48, v70
	v_mov_b32_e32 v53, v2
	v_or_b32_e32 v56, 52, v70
	v_mov_b32_e32 v57, v2
	v_or_b32_e32 v60, 56, v70
	v_mov_b32_e32 v61, v2
	v_or_b32_e32 v66, 60, v70
	v_mov_b32_e32 v67, v2
	v_lshl_add_u64 v[64:65], v[4:5], 0, v[68:69]
	v_lshlrev_b64 v[4:5], 15, v[70:71]
	v_lshlrev_b64 v[8:9], 15, v[8:9]
	v_lshlrev_b64 v[12:13], 15, v[12:13]
	v_lshlrev_b64 v[16:17], 15, v[16:17]
	v_lshlrev_b64 v[20:21], 15, v[20:21]
	v_lshlrev_b64 v[24:25], 15, v[24:25]
	v_lshlrev_b64 v[28:29], 15, v[28:29]
	v_lshlrev_b64 v[32:33], 15, v[32:33]
	v_lshlrev_b64 v[36:37], 15, v[36:37]
	v_lshlrev_b64 v[40:41], 15, v[40:41]
	v_lshlrev_b64 v[44:45], 15, v[44:45]
	v_lshlrev_b64 v[48:49], 15, v[48:49]
	v_lshlrev_b64 v[52:53], 15, v[52:53]
	v_lshlrev_b64 v[56:57], 15, v[56:57]
	v_lshlrev_b64 v[60:61], 15, v[60:61]
	v_lshlrev_b64 v[66:67], 15, v[66:67]
	v_lshl_add_u64 v[4:5], v[64:65], 0, v[4:5]
	v_lshl_add_u64 v[8:9], v[64:65], 0, v[8:9]
	v_lshl_add_u64 v[12:13], v[64:65], 0, v[12:13]
	v_lshl_add_u64 v[16:17], v[64:65], 0, v[16:17]
	v_lshl_add_u64 v[20:21], v[64:65], 0, v[20:21]
	v_lshl_add_u64 v[24:25], v[64:65], 0, v[24:25]
	v_lshl_add_u64 v[28:29], v[64:65], 0, v[28:29]
	v_lshl_add_u64 v[32:33], v[64:65], 0, v[32:33]
	v_lshl_add_u64 v[36:37], v[64:65], 0, v[36:37]
	v_lshl_add_u64 v[40:41], v[64:65], 0, v[40:41]
	v_lshl_add_u64 v[44:45], v[64:65], 0, v[44:45]
	v_lshl_add_u64 v[48:49], v[64:65], 0, v[48:49]
	v_lshl_add_u64 v[52:53], v[64:65], 0, v[52:53]
	v_lshl_add_u64 v[56:57], v[64:65], 0, v[56:57]
	v_lshl_add_u64 v[60:61], v[64:65], 0, v[60:61]
	v_lshl_add_u64 v[64:65], v[64:65], 0, v[66:67]
	global_load_dwordx4 v[4:7], v[4:5], off nt
	s_load_dwordx2 s[18:19], s[8:9], 0x40
	global_load_dwordx4 v[8:11], v[8:9], off nt
	s_waitcnt lgkmcnt(0)
	s_cmp_eq_u64 s[18:19], 0
	global_load_dwordx4 v[12:15], v[12:13], off nt
	s_nop 0
	global_load_dwordx4 v[16:19], v[16:17], off nt
	s_nop 0
	global_load_dwordx4 v[20:23], v[20:21], off nt
	s_nop 0
	global_load_dwordx4 v[24:27], v[24:25], off nt
	s_nop 0
	global_load_dwordx4 v[28:31], v[28:29], off nt
	s_nop 0
	global_load_dwordx4 v[32:35], v[32:33], off nt
	s_nop 0
	global_load_dwordx4 v[36:39], v[36:37], off nt
	s_nop 0
	global_load_dwordx4 v[40:43], v[40:41], off nt
	s_nop 0
	global_load_dwordx4 v[44:47], v[44:45], off nt
	s_nop 0
	global_load_dwordx4 v[48:51], v[48:49], off nt
	s_nop 0
	global_load_dwordx4 v[52:55], v[52:53], off nt
	s_nop 0
	global_load_dwordx4 v[56:59], v[56:57], off nt
	s_nop 0
	global_load_dwordx4 v[60:63], v[60:61], off nt
	s_nop 0
	global_load_dwordx4 v[64:67], v[64:65], off nt
	s_cbranch_scc1 .LBB0_234
	s_lshl_b32 s20, s80, 11
	s_mov_b32 s21, s81
	s_lshl_b64 s[20:21], s[20:21], 2
	s_add_u32 s18, s18, s20
	s_addc_u32 s19, s19, s21
	v_lshl_add_u64 v[70:71], v[70:71], 2, s[18:19]
	global_load_dword v160, v[70:71], off
	global_load_dword v161, v[70:71], off offset:16
	global_load_dword v162, v[70:71], off offset:32
	global_load_dword v163, v[70:71], off offset:48
	global_load_dword v164, v[70:71], off offset:64
	global_load_dword v165, v[70:71], off offset:80
	global_load_dword v166, v[70:71], off offset:96
	global_load_dword v167, v[70:71], off offset:112
	global_load_dword v168, v[70:71], off offset:128
	global_load_dword v169, v[70:71], off offset:144
	global_load_dword v170, v[70:71], off offset:160
	global_load_dword v171, v[70:71], off offset:176
	global_load_dword v172, v[70:71], off offset:192
	global_load_dword v173, v[70:71], off offset:208
	global_load_dword v174, v[70:71], off offset:224
	global_load_dword v175, v[70:71], off offset:240
	s_waitcnt vmcnt(0)
	v_pk_mul_f32 v[6:7], v[6:7], v[160:161] op_sel_hi:[1,0]
	v_pk_mul_f32 v[4:5], v[4:5], v[160:161] op_sel_hi:[1,0]
	v_pk_mul_f32 v[10:11], v[10:11], v[160:161] op_sel:[0,1]
	v_pk_mul_f32 v[8:9], v[8:9], v[160:161] op_sel:[0,1]
	v_pk_mul_f32 v[14:15], v[14:15], v[162:163] op_sel_hi:[1,0]
	v_pk_mul_f32 v[12:13], v[12:13], v[162:163] op_sel_hi:[1,0]
	v_pk_mul_f32 v[18:19], v[18:19], v[162:163] op_sel:[0,1]
	v_pk_mul_f32 v[16:17], v[16:17], v[162:163] op_sel:[0,1]
	v_pk_mul_f32 v[22:23], v[22:23], v[164:165] op_sel_hi:[1,0]
	v_pk_mul_f32 v[20:21], v[20:21], v[164:165] op_sel_hi:[1,0]
	v_pk_mul_f32 v[26:27], v[26:27], v[164:165] op_sel:[0,1]
	v_pk_mul_f32 v[24:25], v[24:25], v[164:165] op_sel:[0,1]
	v_pk_mul_f32 v[30:31], v[30:31], v[166:167] op_sel_hi:[1,0]
	v_pk_mul_f32 v[28:29], v[28:29], v[166:167] op_sel_hi:[1,0]
	v_pk_mul_f32 v[34:35], v[34:35], v[166:167] op_sel:[0,1]
	v_pk_mul_f32 v[32:33], v[32:33], v[166:167] op_sel:[0,1]
	v_pk_mul_f32 v[38:39], v[38:39], v[168:169] op_sel_hi:[1,0]
	v_pk_mul_f32 v[36:37], v[36:37], v[168:169] op_sel_hi:[1,0]
	v_pk_mul_f32 v[42:43], v[42:43], v[168:169] op_sel:[0,1]
	v_pk_mul_f32 v[40:41], v[40:41], v[168:169] op_sel:[0,1]
	v_pk_mul_f32 v[46:47], v[46:47], v[170:171] op_sel_hi:[1,0]
	v_pk_mul_f32 v[44:45], v[44:45], v[170:171] op_sel_hi:[1,0]
	v_pk_mul_f32 v[50:51], v[50:51], v[170:171] op_sel:[0,1]
	v_pk_mul_f32 v[48:49], v[48:49], v[170:171] op_sel:[0,1]
	v_pk_mul_f32 v[54:55], v[54:55], v[172:173] op_sel_hi:[1,0]
	v_pk_mul_f32 v[52:53], v[52:53], v[172:173] op_sel_hi:[1,0]
	v_pk_mul_f32 v[58:59], v[58:59], v[172:173] op_sel:[0,1]
	v_pk_mul_f32 v[56:57], v[56:57], v[172:173] op_sel:[0,1]
	v_pk_mul_f32 v[62:63], v[62:63], v[174:175] op_sel_hi:[1,0]
	v_pk_mul_f32 v[60:61], v[60:61], v[174:175] op_sel_hi:[1,0]
	v_pk_mul_f32 v[66:67], v[66:67], v[174:175] op_sel:[0,1]
	v_pk_mul_f32 v[64:65], v[64:65], v[174:175] op_sel:[0,1]

; #define LAS __attribute__((address_space(3)))
; __device__ __forceinline__ void transpose_item(const float* W, int ldw, int sc0, int k0, const float* kscale, bf16_t* WT, int Kd, int dr0, int nvalid, LAS float* scr, int lane) {
;     const int l16 = lane & 15, kq = lane >> 4;
;     f32x4 v[16];
; #pragma unroll
;     for (int i = 0; i < 16; ++i) { const int kk = 4 * i + kq; v[i] = (f32x4){0.f, 0.f, 0.f, 0.f};
;         if (4 * l16 < nvalid) v[i] = __builtin_nontemporal_load((const f32x4*)(W + (size_t)(k0 + kk) * ldw + sc0 + 4 * l16)); }
;     if (kscale) {
; #pragma unroll
;         for (int i = 0; i < 16; ++i) v[i] = v[i] * kscale[k0 + 4 * i + kq]; }
.LBB0_275:
	s_or_b64 exec, exec, s[12:13]
	s_waitcnt lgkmcnt(0)
	s_cmp_lg_u64 s[8:9], 0
	s_cbranch_scc0 .LBB0_277
	s_lshl_b32 s80, s80, 11
	s_lshl_b64 s[12:13], s[80:81], 2
	s_add_u32 s8, s8, s12
	s_addc_u32 s9, s9, s13
	v_ashrrev_i32_e32 v75, 31, v74
	v_lshl_add_u64 v[4:5], v[74:75], 2, s[8:9]
	global_load_dword v160, v[4:5], off
	global_load_dword v161, v[4:5], off offset:16
	global_load_dword v162, v[4:5], off offset:32
	global_load_dword v163, v[4:5], off offset:48
	global_load_dword v164, v[4:5], off offset:64
	global_load_dword v165, v[4:5], off offset:80
	global_load_dword v166, v[4:5], off offset:96
	global_load_dword v167, v[4:5], off offset:112
	global_load_dword v168, v[4:5], off offset:128
	global_load_dword v169, v[4:5], off offset:144
	global_load_dword v170, v[4:5], off offset:160
	global_load_dword v171, v[4:5], off offset:176
	global_load_dword v172, v[4:5], off offset:192
	global_load_dword v173, v[4:5], off offset:208
	global_load_dword v174, v[4:5], off offset:224
	global_load_dword v175, v[4:5], off offset:240
	s_waitcnt vmcnt(0)
	v_pk_mul_f32 v[12:13], v[12:13], v[160:161] op_sel_hi:[1,0]
	v_pk_mul_f32 v[10:11], v[10:11], v[160:161] op_sel_hi:[1,0]
	v_pk_mul_f32 v[8:9], v[8:9], v[160:161] op_sel:[0,1]
	v_pk_mul_f32 v[6:7], v[6:7], v[160:161] op_sel:[0,1]
	v_pk_mul_f32 v[16:17], v[16:17], v[162:163] op_sel_hi:[1,0]
	v_pk_mul_f32 v[14:15], v[14:15], v[162:163] op_sel_hi:[1,0]
	v_pk_mul_f32 v[20:21], v[20:21], v[162:163] op_sel:[0,1]
	v_pk_mul_f32 v[18:19], v[18:19], v[162:163] op_sel:[0,1]
	v_pk_mul_f32 v[24:25], v[24:25], v[164:165] op_sel_hi:[1,0]
	v_pk_mul_f32 v[22:23], v[22:23], v[164:165] op_sel_hi:[1,0]
	v_pk_mul_f32 v[28:29], v[28:29], v[164:165] op_sel:[0,1]
	v_pk_mul_f32 v[26:27], v[26:27], v[164:165] op_sel:[0,1]
	v_pk_mul_f32 v[32:33], v[32:33], v[166:167] op_sel_hi:[1,0]
	v_pk_mul_f32 v[30:31], v[30:31], v[166:167] op_sel_hi:[1,0]
	v_pk_mul_f32 v[36:37], v[36:37], v[166:167] op_sel:[0,1]
	v_pk_mul_f32 v[34:35], v[34:35], v[166:167] op_sel:[0,1]
	v_pk_mul_f32 v[40:41], v[40:41], v[168:169] op_sel_hi:[1,0]
	v_pk_mul_f32 v[38:39], v[38:39], v[168:169] op_sel_hi:[1,0]
	v_pk_mul_f32 v[44:45], v[44:45], v[168:169] op_sel:[0,1]
	v_pk_mul_f32 v[42:43], v[42:43], v[168:169] op_sel:[0,1]
	v_pk_mul_f32 v[48:49], v[48:49], v[170:171] op_sel_hi:[1,0]
	v_pk_mul_f32 v[46:47], v[46:47], v[170:171] op_sel_hi:[1,0]
	v_pk_mul_f32 v[52:53], v[52:53], v[170:171] op_sel:[0,1]
	v_pk_mul_f32 v[50:51], v[50:51], v[170:171] op_sel:[0,1]
	v_pk_mul_f32 v[56:57], v[56:57], v[172:173] op_sel_hi:[1,0]
	v_pk_mul_f32 v[54:55], v[54:55], v[172:173] op_sel_hi:[1,0]
	v_pk_mul_f32 v[60:61], v[60:61], v[172:173] op_sel:[0,1]
	v_pk_mul_f32 v[58:59], v[58:59], v[172:173] op_sel:[0,1]
	v_pk_mul_f32 v[64:65], v[64:65], v[174:175] op_sel_hi:[1,0]
	v_pk_mul_f32 v[62:63], v[62:63], v[174:175] op_sel_hi:[1,0]
	v_pk_mul_f32 v[68:69], v[68:69], v[174:175] op_sel:[0,1]
	v_pk_mul_f32 v[66:67], v[66:67], v[174:175] op_sel:[0,1]

; #define LAS __attribute__((address_space(3)))
; __device__ __forceinline__ void transpose_item(const float* W, int ldw, int sc0, int k0, const float* kscale, bf16_t* WT, int Kd, int dr0, int nvalid, LAS float* scr, int lane) {
;     const int l16 = lane & 15, kq = lane >> 4;
;     f32x4 v[16];
; #pragma unroll
;     for (int i = 0; i < 16; ++i) { const int kk = 4 * i + kq; v[i] = (f32x4){0.f, 0.f, 0.f, 0.f};
;         if (4 * l16 < nvalid) v[i] = __builtin_nontemporal_load((const f32x4*)(W + (size_t)(k0 + kk) * ldw + sc0 + 4 * l16)); }
;     if (kscale) {
; #pragma unroll
;         for (int i = 0; i < 16; ++i) v[i] = v[i] * kscale[k0 + 4 * i + kq]; }
; __device__ __forceinline__ void conv_item(CArgs* a, int l, int r, LAS float* scr, int lane) {
;     ...
;     if (r < IT_UP) { const int kb = r / 128, nb = r - kb * 128;
;         transpose_item(a->in[28] + (size_t)l * D * DFF, DFF, 64 * nb, 64 * kb, a->in[8] + l * D, (bf16_t*)(lw + LW_UP), D, 64 * nb, 64, scr, lane); return; }
.LBB0_925:
	s_andn2_saveexec_b64 s[74:75], s[74:75]
	s_cbranch_execz .LBB0_929
	s_load_dwordx2 s[78:79], s[38:39], 0xe0
	s_load_dwordx2 s[88:89], s[38:39], 0x40
	v_add_u32_e32 v4, 0xffffd5d1, v4
	v_add_u32_e32 v3, 0xfff57440, v100
	v_lshrrev_b32_e32 v4, 1, v4
	v_and_b32_e32 v3, 0x1fc0, v3
	s_waitcnt lgkmcnt(0)
	s_add_u32 s78, s78, s20
	v_and_b32_e32 v84, 0x7fffffc0, v4
	s_addc_u32 s79, s79, s21
	v_or_b32_e32 v68, v84, v71
	v_lshlrev_b32_e32 v4, 2, v3
	v_mov_b32_e32 v5, v2
	v_lshl_add_u64 v[4:5], s[78:79], 0, v[4:5]
	v_lshlrev_b32_e32 v6, 2, v70
	v_mov_b32_e32 v7, v2
	v_mov_b32_e32 v69, v2
	v_or_b32_e32 v8, 4, v68
	v_mov_b32_e32 v9, v2
	v_or_b32_e32 v12, 8, v68
	v_mov_b32_e32 v13, v2
	v_or_b32_e32 v16, 12, v68
	v_mov_b32_e32 v17, v2
	v_or_b32_e32 v20, 16, v68
	v_mov_b32_e32 v21, v2
	v_or_b32_e32 v24, 20, v68
	v_mov_b32_e32 v25, v2
	v_or_b32_e32 v28, 24, v68
	v_mov_b32_e32 v29, v2
	v_or_b32_e32 v32, 28, v68
	v_mov_b32_e32 v33, v2
	v_or_b32_e32 v36, 32, v68
	v_mov_b32_e32 v37, v2
	v_or_b32_e32 v40, 36, v68
	v_mov_b32_e32 v41, v2
	v_or_b32_e32 v44, 40, v68
	v_mov_b32_e32 v45, v2
	v_or_b32_e32 v48, 44, v68
	v_mov_b32_e32 v49, v2
	v_or_b32_e32 v52, 48, v68
	v_mov_b32_e32 v53, v2
	v_or_b32_e32 v56, 52, v68
	v_mov_b32_e32 v57, v2
	v_or_b32_e32 v60, 56, v68
	v_mov_b32_e32 v61, v2
	v_or_b32_e32 v66, 60, v68
	v_mov_b32_e32 v67, v2
	v_lshl_add_u64 v[64:65], v[4:5], 0, v[6:7]
	v_lshlrev_b64 v[4:5], 15, v[68:69]
	v_lshlrev_b64 v[8:9], 15, v[8:9]
	v_lshlrev_b64 v[12:13], 15, v[12:13]
	v_lshlrev_b64 v[16:17], 15, v[16:17]
	v_lshlrev_b64 v[20:21], 15, v[20:21]
	v_lshlrev_b64 v[24:25], 15, v[24:25]
	v_lshlrev_b64 v[28:29], 15, v[28:29]
	v_lshlrev_b64 v[32:33], 15, v[32:33]
	v_lshlrev_b64 v[36:37], 15, v[36:37]
	v_lshlrev_b64 v[40:41], 15, v[40:41]
	v_lshlrev_b64 v[44:45], 15, v[44:45]
	v_lshlrev_b64 v[48:49], 15, v[48:49]
	v_lshlrev_b64 v[52:53], 15, v[52:53]
	v_lshlrev_b64 v[56:57], 15, v[56:57]
	v_lshlrev_b64 v[60:61], 15, v[60:61]
	v_lshlrev_b64 v[66:67], 15, v[66:67]
	v_lshl_add_u64 v[4:5], v[64:65], 0, v[4:5]
	v_lshl_add_u64 v[8:9], v[64:65], 0, v[8:9]
	v_lshl_add_u64 v[12:13], v[64:65], 0, v[12:13]
	v_lshl_add_u64 v[16:17], v[64:65], 0, v[16:17]
	v_lshl_add_u64 v[20:21], v[64:65], 0, v[20:21]
	v_lshl_add_u64 v[24:25], v[64:65], 0, v[24:25]
	v_lshl_add_u64 v[28:29], v[64:65], 0, v[28:29]
	v_lshl_add_u64 v[32:33], v[64:65], 0, v[32:33]
	v_lshl_add_u64 v[36:37], v[64:65], 0, v[36:37]
	v_lshl_add_u64 v[40:41], v[64:65], 0, v[40:41]
	v_lshl_add_u64 v[44:45], v[64:65], 0, v[44:45]
	v_lshl_add_u64 v[48:49], v[64:65], 0, v[48:49]
	v_lshl_add_u64 v[52:53], v[64:65], 0, v[52:53]
	v_lshl_add_u64 v[56:57], v[64:65], 0, v[56:57]
	v_lshl_add_u64 v[60:61], v[64:65], 0, v[60:61]
	v_lshl_add_u64 v[64:65], v[64:65], 0, v[66:67]
	global_load_dwordx4 v[4:7], v[4:5], off nt
	s_cmp_eq_u64 s[88:89], 0
	global_load_dwordx4 v[8:11], v[8:9], off nt
	s_nop 0
	global_load_dwordx4 v[12:15], v[12:13], off nt
	s_nop 0
	global_load_dwordx4 v[16:19], v[16:17], off nt
	s_nop 0
	global_load_dwordx4 v[20:23], v[20:21], off nt
	s_nop 0
	global_load_dwordx4 v[24:27], v[24:25], off nt
	s_nop 0
	global_load_dwordx4 v[28:31], v[28:29], off nt
	s_nop 0
	global_load_dwordx4 v[32:35], v[32:33], off nt
	s_nop 0
	global_load_dwordx4 v[36:39], v[36:37], off nt
	s_nop 0
	global_load_dwordx4 v[40:43], v[40:41], off nt
	s_nop 0
	global_load_dwordx4 v[44:47], v[44:45], off nt
	s_nop 0
	global_load_dwordx4 v[48:51], v[48:49], off nt
	s_nop 0
	global_load_dwordx4 v[52:55], v[52:53], off nt
	s_nop 0
	global_load_dwordx4 v[56:59], v[56:57], off nt
	s_nop 0
	global_load_dwordx4 v[60:63], v[60:61], off nt
	s_nop 0
	global_load_dwordx4 v[64:67], v[64:65], off nt
	s_cbranch_scc1 .LBB0_928
	s_lshl_b64 s[78:79], s[22:23], 2
	s_add_u32 s78, s88, s78
	s_addc_u32 s79, s89, s79
	v_lshl_add_u64 v[68:69], v[68:69], 2, s[78:79]
	global_load_dword v160, v[68:69], off
	global_load_dword v161, v[68:69], off offset:16
	global_load_dword v162, v[68:69], off offset:32
	global_load_dword v163, v[68:69], off offset:48
	global_load_dword v164, v[68:69], off offset:64
	global_load_dword v165, v[68:69], off offset:80
	global_load_dword v166, v[68:69], off offset:96
	global_load_dword v167, v[68:69], off offset:112
	global_load_dword v168, v[68:69], off offset:128
	global_load_dword v169, v[68:69], off offset:144
	global_load_dword v170, v[68:69], off offset:160
	global_load_dword v171, v[68:69], off offset:176
	global_load_dword v172, v[68:69], off offset:192
	global_load_dword v173, v[68:69], off offset:208
	global_load_dword v174, v[68:69], off offset:224
	global_load_dword v175, v[68:69], off offset:240
	s_waitcnt vmcnt(0)
	v_pk_mul_f32 v[6:7], v[6:7], v[160:161] op_sel_hi:[1,0]
	v_pk_mul_f32 v[4:5], v[4:5], v[160:161] op_sel_hi:[1,0]
	v_pk_mul_f32 v[10:11], v[10:11], v[160:161] op_sel:[0,1]
	v_pk_mul_f32 v[8:9], v[8:9], v[160:161] op_sel:[0,1]
	v_pk_mul_f32 v[14:15], v[14:15], v[162:163] op_sel_hi:[1,0]
	v_pk_mul_f32 v[12:13], v[12:13], v[162:163] op_sel_hi:[1,0]
	v_pk_mul_f32 v[18:19], v[18:19], v[162:163] op_sel:[0,1]
	v_pk_mul_f32 v[16:17], v[16:17], v[162:163] op_sel:[0,1]
	v_pk_mul_f32 v[22:23], v[22:23], v[164:165] op_sel_hi:[1,0]
	v_pk_mul_f32 v[20:21], v[20:21], v[164:165] op_sel_hi:[1,0]
	v_pk_mul_f32 v[26:27], v[26:27], v[164:165] op_sel:[0,1]
	v_pk_mul_f32 v[24:25], v[24:25], v[164:165] op_sel:[0,1]
	v_pk_mul_f32 v[30:31], v[30:31], v[166:167] op_sel_hi:[1,0]
	v_pk_mul_f32 v[28:29], v[28:29], v[166:167] op_sel_hi:[1,0]
	v_pk_mul_f32 v[34:35], v[34:35], v[166:167] op_sel:[0,1]
	v_pk_mul_f32 v[32:33], v[32:33], v[166:167] op_sel:[0,1]
	v_pk_mul_f32 v[38:39], v[38:39], v[168:169] op_sel_hi:[1,0]
	v_pk_mul_f32 v[36:37], v[36:37], v[168:169] op_sel_hi:[1,0]
	v_pk_mul_f32 v[42:43], v[42:43], v[168:169] op_sel:[0,1]
	v_pk_mul_f32 v[40:41], v[40:41], v[168:169] op_sel:[0,1]
	v_pk_mul_f32 v[46:47], v[46:47], v[170:171] op_sel_hi:[1,0]
	v_pk_mul_f32 v[44:45], v[44:45], v[170:171] op_sel_hi:[1,0]
	v_pk_mul_f32 v[50:51], v[50:51], v[170:171] op_sel:[0,1]
	v_pk_mul_f32 v[48:49], v[48:49], v[170:171] op_sel:[0,1]
	v_pk_mul_f32 v[54:55], v[54:55], v[172:173] op_sel_hi:[1,0]
	v_pk_mul_f32 v[52:53], v[52:53], v[172:173] op_sel_hi:[1,0]
	v_pk_mul_f32 v[58:59], v[58:59], v[172:173] op_sel:[0,1]
	v_pk_mul_f32 v[56:57], v[56:57], v[172:173] op_sel:[0,1]
	v_pk_mul_f32 v[62:63], v[62:63], v[174:175] op_sel_hi:[1,0]
	v_pk_mul_f32 v[60:61], v[60:61], v[174:175] op_sel_hi:[1,0]
	v_pk_mul_f32 v[66:67], v[66:67], v[174:175] op_sel:[0,1]
	v_pk_mul_f32 v[64:65], v[64:65], v[174:175] op_sel:[0,1]

; #define LAS __attribute__((address_space(3)))
; __device__ __forceinline__ void transpose_item(const float* W, int ldw, int sc0, int k0, const float* kscale, bf16_t* WT, int Kd, int dr0, int nvalid, LAS float* scr, int lane) {
;     const int l16 = lane & 15, kq = lane >> 4;
;     f32x4 v[16];
; #pragma unroll
;     for (int i = 0; i < 16; ++i) { const int kk = 4 * i + kq; v[i] = (f32x4){0.f, 0.f, 0.f, 0.f};
;         if (4 * l16 < nvalid) v[i] = __builtin_nontemporal_load((const f32x4*)(W + (size_t)(k0 + kk) * ldw + sc0 + 4 * l16)); }
;     if (kscale) {
; #pragma unroll
;         for (int i = 0; i < 16; ++i) v[i] = v[i] * kscale[k0 + 4 * i + kq]; }
; __device__ __forceinline__ void conv_item(CArgs* a, int l, int r, LAS float* scr, int lane) {
;     ...
;     if (r < IT_W1) { const int kb = r / 257, nb = r - kb * 257; const int dr0 = 64 * nb; const int sc0 = dr0 < 10240 ? dr0 : (dr0 < NPROJ ? dr0 + 16 : 10240);
;         transpose_item(a->in[10] + (size_t)l * D * NIN, NIN, sc0, 64 * kb, a->in[7] + l * D, (bf16_t*)(lw + LW_W1), D, dr0, nb == 256 ? 16 : 64, scr, lane); return; }
.LBB0_969:
	s_or_b64 exec, exec, s[76:77]
	s_waitcnt lgkmcnt(0)
	s_cmp_lg_u64 s[74:75], 0
	s_cbranch_scc0 .LBB0_971
	s_lshl_b64 s[76:77], s[22:23], 2
	s_add_u32 s74, s74, s76
	s_addc_u32 s75, s75, s77
	v_ashrrev_i32_e32 v87, 31, v86
	v_lshl_add_u64 v[4:5], v[86:87], 2, s[74:75]
	global_load_dword v160, v[4:5], off
	global_load_dword v161, v[4:5], off offset:16
	global_load_dword v162, v[4:5], off offset:32
	global_load_dword v163, v[4:5], off offset:48
	global_load_dword v164, v[4:5], off offset:64
	global_load_dword v165, v[4:5], off offset:80
	global_load_dword v166, v[4:5], off offset:96
	global_load_dword v167, v[4:5], off offset:112
	global_load_dword v168, v[4:5], off offset:128
	global_load_dword v169, v[4:5], off offset:144
	global_load_dword v170, v[4:5], off offset:160
	global_load_dword v171, v[4:5], off offset:176
	global_load_dword v172, v[4:5], off offset:192
	global_load_dword v173, v[4:5], off offset:208
	global_load_dword v174, v[4:5], off offset:224
	global_load_dword v175, v[4:5], off offset:240
	s_waitcnt vmcnt(0)
	v_pk_mul_f32 v[12:13], v[12:13], v[160:161] op_sel_hi:[1,0]
	v_pk_mul_f32 v[10:11], v[10:11], v[160:161] op_sel_hi:[1,0]
	v_pk_mul_f32 v[8:9], v[8:9], v[160:161] op_sel:[0,1]
	v_pk_mul_f32 v[6:7], v[6:7], v[160:161] op_sel:[0,1]
	v_pk_mul_f32 v[16:17], v[16:17], v[162:163] op_sel_hi:[1,0]
	v_pk_mul_f32 v[14:15], v[14:15], v[162:163] op_sel_hi:[1,0]
	v_pk_mul_f32 v[20:21], v[20:21], v[162:163] op_sel:[0,1]
	v_pk_mul_f32 v[18:19], v[18:19], v[162:163] op_sel:[0,1]
	v_pk_mul_f32 v[24:25], v[24:25], v[164:165] op_sel_hi:[1,0]
	v_pk_mul_f32 v[22:23], v[22:23], v[164:165] op_sel_hi:[1,0]
	v_pk_mul_f32 v[28:29], v[28:29], v[164:165] op_sel:[0,1]
	v_pk_mul_f32 v[26:27], v[26:27], v[164:165] op_sel:[0,1]
	v_pk_mul_f32 v[32:33], v[32:33], v[166:167] op_sel_hi:[1,0]
	v_pk_mul_f32 v[30:31], v[30:31], v[166:167] op_sel_hi:[1,0]
	v_pk_mul_f32 v[36:37], v[36:37], v[166:167] op_sel:[0,1]
	v_pk_mul_f32 v[34:35], v[34:35], v[166:167] op_sel:[0,1]
	v_pk_mul_f32 v[40:41], v[40:41], v[168:169] op_sel_hi:[1,0]
	v_pk_mul_f32 v[38:39], v[38:39], v[168:169] op_sel_hi:[1,0]
	v_pk_mul_f32 v[44:45], v[44:45], v[168:169] op_sel:[0,1]
	v_pk_mul_f32 v[42:43], v[42:43], v[168:169] op_sel:[0,1]
	v_pk_mul_f32 v[48:49], v[48:49], v[170:171] op_sel_hi:[1,0]
	v_pk_mul_f32 v[46:47], v[46:47], v[170:171] op_sel_hi:[1,0]
	v_pk_mul_f32 v[52:53], v[52:53], v[170:171] op_sel:[0,1]
	v_pk_mul_f32 v[50:51], v[50:51], v[170:171] op_sel:[0,1]
	v_pk_mul_f32 v[56:57], v[56:57], v[172:173] op_sel_hi:[1,0]
	v_pk_mul_f32 v[54:55], v[54:55], v[172:173] op_sel_hi:[1,0]
	v_pk_mul_f32 v[60:61], v[60:61], v[172:173] op_sel:[0,1]
	v_pk_mul_f32 v[58:59], v[58:59], v[172:173] op_sel:[0,1]
	v_pk_mul_f32 v[64:65], v[64:65], v[174:175] op_sel_hi:[1,0]
	v_pk_mul_f32 v[62:63], v[62:63], v[174:175] op_sel_hi:[1,0]
	v_pk_mul_f32 v[68:69], v[68:69], v[174:175] op_sel:[0,1]
	v_pk_mul_f32 v[66:67], v[66:67], v[174:175] op_sel:[0,1]

; #define LAS __attribute__((address_space(3)))
; __device__ __forceinline__ void transpose_item(const float* W, int ldw, int sc0, int k0, const float* kscale, bf16_t* WT, int Kd, int dr0, int nvalid, LAS float* scr, int lane) {
;     const int l16 = lane & 15, kq = lane >> 4;
;     f32x4 v[16];
; #pragma unroll
;     for (int i = 0; i < 16; ++i) { const int kk = 4 * i + kq; v[i] = (f32x4){0.f, 0.f, 0.f, 0.f};
;         if (4 * l16 < nvalid) v[i] = __builtin_nontemporal_load((const f32x4*)(W + (size_t)(k0 + kk) * ldw + sc0 + 4 * l16)); }
;     if (kscale) {
; #pragma unroll
;         for (int i = 0; i < 16; ++i) v[i] = v[i] * kscale[k0 + 4 * i + kq]; }
; __device__ __forceinline__ void conv_item(CArgs* a, int l, int r, LAS float* scr, int lane) {
;     ...
;     if (r < IT_UP) { const int kb = r / 128, nb = r - kb * 128;
;         transpose_item(a->in[28] + (size_t)l * D * DFF, DFF, 64 * nb, 64 * kb, a->in[8] + l * D, (bf16_t*)(lw + LW_UP), D, 64 * nb, 64, scr, lane); return; }
.LBB0_1368:
	s_andn2_saveexec_b64 s[36:37], s[36:37]
	s_cbranch_execz .LBB0_1372
	s_load_dwordx2 s[38:39], s[8:9], 0xe0
	v_add_u32_e32 v4, 0xffffd5e0, v71
	v_add_u32_e32 v3, 0xfffdf800, v98
	v_lshrrev_b32_e32 v4, 1, v4
	v_and_b32_e32 v3, 0x1fc0, v3
	s_waitcnt lgkmcnt(0)
	s_add_u32 s38, s38, s16
	v_and_b32_e32 v82, 0x7fffffc0, v4
	s_addc_u32 s39, s39, s17
	v_or_b32_e32 v68, v82, v73
	v_lshlrev_b32_e32 v4, 2, v3
	v_mov_b32_e32 v5, v2
	v_lshl_add_u64 v[4:5], s[38:39], 0, v[4:5]
	v_lshlrev_b32_e32 v6, 2, v70
	v_mov_b32_e32 v7, v2
	v_mov_b32_e32 v69, v2
	v_or_b32_e32 v8, 4, v68
	v_mov_b32_e32 v9, v2
	v_or_b32_e32 v12, 8, v68
	v_mov_b32_e32 v13, v2
	v_or_b32_e32 v16, 12, v68
	v_mov_b32_e32 v17, v2
	v_or_b32_e32 v20, 16, v68
	v_mov_b32_e32 v21, v2
	v_or_b32_e32 v24, 20, v68
	v_mov_b32_e32 v25, v2
	v_or_b32_e32 v28, 24, v68
	v_mov_b32_e32 v29, v2
	v_or_b32_e32 v32, 28, v68
	v_mov_b32_e32 v33, v2
	v_or_b32_e32 v36, 32, v68
	v_mov_b32_e32 v37, v2
	v_or_b32_e32 v40, 36, v68
	v_mov_b32_e32 v41, v2
	v_or_b32_e32 v44, 40, v68
	v_mov_b32_e32 v45, v2
	v_or_b32_e32 v48, 44, v68
	v_mov_b32_e32 v49, v2
	v_or_b32_e32 v52, 48, v68
	v_mov_b32_e32 v53, v2
	v_or_b32_e32 v56, 52, v68
	v_mov_b32_e32 v57, v2
	v_or_b32_e32 v60, 56, v68
	v_mov_b32_e32 v61, v2
	v_or_b32_e32 v66, 60, v68
	v_mov_b32_e32 v67, v2
	v_lshl_add_u64 v[64:65], v[4:5], 0, v[6:7]
	v_lshlrev_b64 v[4:5], 15, v[68:69]
	v_lshlrev_b64 v[8:9], 15, v[8:9]
	v_lshlrev_b64 v[12:13], 15, v[12:13]
	v_lshlrev_b64 v[16:17], 15, v[16:17]
	v_lshlrev_b64 v[20:21], 15, v[20:21]
	v_lshlrev_b64 v[24:25], 15, v[24:25]
	v_lshlrev_b64 v[28:29], 15, v[28:29]
	v_lshlrev_b64 v[32:33], 15, v[32:33]
	v_lshlrev_b64 v[36:37], 15, v[36:37]
	v_lshlrev_b64 v[40:41], 15, v[40:41]
	v_lshlrev_b64 v[44:45], 15, v[44:45]
	v_lshlrev_b64 v[48:49], 15, v[48:49]
	v_lshlrev_b64 v[52:53], 15, v[52:53]
	v_lshlrev_b64 v[56:57], 15, v[56:57]
	v_lshlrev_b64 v[60:61], 15, v[60:61]
	v_lshlrev_b64 v[66:67], 15, v[66:67]
	v_lshl_add_u64 v[4:5], v[64:65], 0, v[4:5]
	v_lshl_add_u64 v[8:9], v[64:65], 0, v[8:9]
	v_lshl_add_u64 v[12:13], v[64:65], 0, v[12:13]
	v_lshl_add_u64 v[16:17], v[64:65], 0, v[16:17]
	v_lshl_add_u64 v[20:21], v[64:65], 0, v[20:21]
	v_lshl_add_u64 v[24:25], v[64:65], 0, v[24:25]
	v_lshl_add_u64 v[28:29], v[64:65], 0, v[28:29]
	v_lshl_add_u64 v[32:33], v[64:65], 0, v[32:33]
	v_lshl_add_u64 v[36:37], v[64:65], 0, v[36:37]
	v_lshl_add_u64 v[40:41], v[64:65], 0, v[40:41]
	v_lshl_add_u64 v[44:45], v[64:65], 0, v[44:45]
	v_lshl_add_u64 v[48:49], v[64:65], 0, v[48:49]
	v_lshl_add_u64 v[52:53], v[64:65], 0, v[52:53]
	v_lshl_add_u64 v[56:57], v[64:65], 0, v[56:57]
	v_lshl_add_u64 v[60:61], v[64:65], 0, v[60:61]
	v_lshl_add_u64 v[64:65], v[64:65], 0, v[66:67]
	global_load_dwordx4 v[4:7], v[4:5], off nt
	s_load_dwordx2 s[38:39], s[8:9], 0x40
	global_load_dwordx4 v[8:11], v[8:9], off nt
	s_waitcnt lgkmcnt(0)
	s_cmp_eq_u64 s[38:39], 0
	global_load_dwordx4 v[12:15], v[12:13], off nt
	s_nop 0
	global_load_dwordx4 v[16:19], v[16:17], off nt
	s_nop 0
	global_load_dwordx4 v[20:23], v[20:21], off nt
	s_nop 0
	global_load_dwordx4 v[24:27], v[24:25], off nt
	s_nop 0
	global_load_dwordx4 v[28:31], v[28:29], off nt
	s_nop 0
	global_load_dwordx4 v[32:35], v[32:33], off nt
	s_nop 0
	global_load_dwordx4 v[36:39], v[36:37], off nt
	s_nop 0
	global_load_dwordx4 v[40:43], v[40:41], off nt
	s_nop 0
	global_load_dwordx4 v[44:47], v[44:45], off nt
	s_nop 0
	global_load_dwordx4 v[48:51], v[48:49], off nt
	s_nop 0
	global_load_dwordx4 v[52:55], v[52:53], off nt
	s_nop 0
	global_load_dwordx4 v[56:59], v[56:57], off nt
	s_nop 0
	global_load_dwordx4 v[60:63], v[60:61], off nt
	s_nop 0
	global_load_dwordx4 v[64:67], v[64:65], off nt
	s_cbranch_scc1 .LBB0_1371
	s_lshl_b64 s[44:45], s[80:81], 2
	s_add_u32 s38, s38, s44
	s_addc_u32 s39, s39, s45
	v_lshl_add_u64 v[68:69], v[68:69], 2, s[38:39]
	global_load_dword v160, v[68:69], off
	global_load_dword v161, v[68:69], off offset:16
	global_load_dword v162, v[68:69], off offset:32
	global_load_dword v163, v[68:69], off offset:48
	global_load_dword v164, v[68:69], off offset:64
	global_load_dword v165, v[68:69], off offset:80
	global_load_dword v166, v[68:69], off offset:96
	global_load_dword v167, v[68:69], off offset:112
	global_load_dword v168, v[68:69], off offset:128
	global_load_dword v169, v[68:69], off offset:144
	global_load_dword v170, v[68:69], off offset:160
	global_load_dword v171, v[68:69], off offset:176
	global_load_dword v172, v[68:69], off offset:192
	global_load_dword v173, v[68:69], off offset:208
	global_load_dword v174, v[68:69], off offset:224
	global_load_dword v175, v[68:69], off offset:240
	s_waitcnt vmcnt(0)
	v_pk_mul_f32 v[6:7], v[6:7], v[160:161] op_sel_hi:[1,0]
	v_pk_mul_f32 v[4:5], v[4:5], v[160:161] op_sel_hi:[1,0]
	v_pk_mul_f32 v[10:11], v[10:11], v[160:161] op_sel:[0,1]
	v_pk_mul_f32 v[8:9], v[8:9], v[160:161] op_sel:[0,1]
	v_pk_mul_f32 v[14:15], v[14:15], v[162:163] op_sel_hi:[1,0]
	v_pk_mul_f32 v[12:13], v[12:13], v[162:163] op_sel_hi:[1,0]
	v_pk_mul_f32 v[18:19], v[18:19], v[162:163] op_sel:[0,1]
	v_pk_mul_f32 v[16:17], v[16:17], v[162:163] op_sel:[0,1]
	v_pk_mul_f32 v[22:23], v[22:23], v[164:165] op_sel_hi:[1,0]
	v_pk_mul_f32 v[20:21], v[20:21], v[164:165] op_sel_hi:[1,0]
	v_pk_mul_f32 v[26:27], v[26:27], v[164:165] op_sel:[0,1]
	v_pk_mul_f32 v[24:25], v[24:25], v[164:165] op_sel:[0,1]
	v_pk_mul_f32 v[30:31], v[30:31], v[166:167] op_sel_hi:[1,0]
	v_pk_mul_f32 v[28:29], v[28:29], v[166:167] op_sel_hi:[1,0]
	v_pk_mul_f32 v[34:35], v[34:35], v[166:167] op_sel:[0,1]
	v_pk_mul_f32 v[32:33], v[32:33], v[166:167] op_sel:[0,1]
	v_pk_mul_f32 v[38:39], v[38:39], v[168:169] op_sel_hi:[1,0]
	v_pk_mul_f32 v[36:37], v[36:37], v[168:169] op_sel_hi:[1,0]
	v_pk_mul_f32 v[42:43], v[42:43], v[168:169] op_sel:[0,1]
	v_pk_mul_f32 v[40:41], v[40:41], v[168:169] op_sel:[0,1]
	v_pk_mul_f32 v[46:47], v[46:47], v[170:171] op_sel_hi:[1,0]
	v_pk_mul_f32 v[44:45], v[44:45], v[170:171] op_sel_hi:[1,0]
	v_pk_mul_f32 v[50:51], v[50:51], v[170:171] op_sel:[0,1]
	v_pk_mul_f32 v[48:49], v[48:49], v[170:171] op_sel:[0,1]
	v_pk_mul_f32 v[54:55], v[54:55], v[172:173] op_sel_hi:[1,0]
	v_pk_mul_f32 v[52:53], v[52:53], v[172:173] op_sel_hi:[1,0]
	v_pk_mul_f32 v[58:59], v[58:59], v[172:173] op_sel:[0,1]
	v_pk_mul_f32 v[56:57], v[56:57], v[172:173] op_sel:[0,1]
	v_pk_mul_f32 v[62:63], v[62:63], v[174:175] op_sel_hi:[1,0]
	v_pk_mul_f32 v[60:61], v[60:61], v[174:175] op_sel_hi:[1,0]
	v_pk_mul_f32 v[66:67], v[66:67], v[174:175] op_sel:[0,1]
	v_pk_mul_f32 v[64:65], v[64:65], v[174:175] op_sel:[0,1]

; #define LAS __attribute__((address_space(3)))
; __device__ __forceinline__ void transpose_item(const float* W, int ldw, int sc0, int k0, const float* kscale, bf16_t* WT, int Kd, int dr0, int nvalid, LAS float* scr, int lane) {
;     const int l16 = lane & 15, kq = lane >> 4;
;     f32x4 v[16];
; #pragma unroll
;     for (int i = 0; i < 16; ++i) { const int kk = 4 * i + kq; v[i] = (f32x4){0.f, 0.f, 0.f, 0.f};
;         if (4 * l16 < nvalid) v[i] = __builtin_nontemporal_load((const f32x4*)(W + (size_t)(k0 + kk) * ldw + sc0 + 4 * l16)); }
;     if (kscale) {
; #pragma unroll
;         for (int i = 0; i < 16; ++i) v[i] = v[i] * kscale[k0 + 4 * i + kq]; }
; __device__ __forceinline__ void conv_item(CArgs* a, int l, int r, LAS float* scr, int lane) {
;     ...
;     if (r < IT_W1) { const int kb = r / 257, nb = r - kb * 257; const int dr0 = 64 * nb; const int sc0 = dr0 < 10240 ? dr0 : (dr0 < NPROJ ? dr0 + 16 : 10240);
;         transpose_item(a->in[10] + (size_t)l * D * NIN, NIN, sc0, 64 * kb, a->in[7] + l * D, (bf16_t*)(lw + LW_W1), D, dr0, nb == 256 ? 16 : 64, scr, lane); return; }
.LBB0_1412:
	s_or_b64 exec, exec, s[34:35]
	s_waitcnt lgkmcnt(0)
	s_cmp_lg_u64 s[30:31], 0
	s_cbranch_scc0 .LBB0_1414
	s_lshl_b64 s[34:35], s[80:81], 2
	s_add_u32 s30, s30, s34
	s_addc_u32 s31, s31, s35
	v_ashrrev_i32_e32 v85, 31, v84
	v_lshl_add_u64 v[4:5], v[84:85], 2, s[30:31]
	global_load_dword v160, v[4:5], off
	global_load_dword v161, v[4:5], off offset:16
	global_load_dword v162, v[4:5], off offset:32
	global_load_dword v163, v[4:5], off offset:48
	global_load_dword v164, v[4:5], off offset:64
	global_load_dword v165, v[4:5], off offset:80
	global_load_dword v166, v[4:5], off offset:96
	global_load_dword v167, v[4:5], off offset:112
	global_load_dword v168, v[4:5], off offset:128
	global_load_dword v169, v[4:5], off offset:144
	global_load_dword v170, v[4:5], off offset:160
	global_load_dword v171, v[4:5], off offset:176
	global_load_dword v172, v[4:5], off offset:192
	global_load_dword v173, v[4:5], off offset:208
	global_load_dword v174, v[4:5], off offset:224
	global_load_dword v175, v[4:5], off offset:240
	s_waitcnt vmcnt(0)
	v_pk_mul_f32 v[12:13], v[12:13], v[160:161] op_sel_hi:[1,0]
	v_pk_mul_f32 v[10:11], v[10:11], v[160:161] op_sel_hi:[1,0]
	v_pk_mul_f32 v[8:9], v[8:9], v[160:161] op_sel:[0,1]
	v_pk_mul_f32 v[6:7], v[6:7], v[160:161] op_sel:[0,1]
	v_pk_mul_f32 v[16:17], v[16:17], v[162:163] op_sel_hi:[1,0]
	v_pk_mul_f32 v[14:15], v[14:15], v[162:163] op_sel_hi:[1,0]
	v_pk_mul_f32 v[20:21], v[20:21], v[162:163] op_sel:[0,1]
	v_pk_mul_f32 v[18:19], v[18:19], v[162:163] op_sel:[0,1]
	v_pk_mul_f32 v[24:25], v[24:25], v[164:165] op_sel_hi:[1,0]
	v_pk_mul_f32 v[22:23], v[22:23], v[164:165] op_sel_hi:[1,0]
	v_pk_mul_f32 v[28:29], v[28:29], v[164:165] op_sel:[0,1]
	v_pk_mul_f32 v[26:27], v[26:27], v[164:165] op_sel:[0,1]
	v_pk_mul_f32 v[32:33], v[32:33], v[166:167] op_sel_hi:[1,0]
	v_pk_mul_f32 v[30:31], v[30:31], v[166:167] op_sel_hi:[1,0]
	v_pk_mul_f32 v[36:37], v[36:37], v[166:167] op_sel:[0,1]
	v_pk_mul_f32 v[34:35], v[34:35], v[166:167] op_sel:[0,1]
	v_pk_mul_f32 v[40:41], v[40:41], v[168:169] op_sel_hi:[1,0]
	v_pk_mul_f32 v[38:39], v[38:39], v[168:169] op_sel_hi:[1,0]
	v_pk_mul_f32 v[44:45], v[44:45], v[168:169] op_sel:[0,1]
	v_pk_mul_f32 v[42:43], v[42:43], v[168:169] op_sel:[0,1]
	v_pk_mul_f32 v[48:49], v[48:49], v[170:171] op_sel_hi:[1,0]
	v_pk_mul_f32 v[46:47], v[46:47], v[170:171] op_sel_hi:[1,0]
	v_pk_mul_f32 v[52:53], v[52:53], v[170:171] op_sel:[0,1]
	v_pk_mul_f32 v[50:51], v[50:51], v[170:171] op_sel:[0,1]
	v_pk_mul_f32 v[56:57], v[56:57], v[172:173] op_sel_hi:[1,0]
	v_pk_mul_f32 v[54:55], v[54:55], v[172:173] op_sel_hi:[1,0]
	v_pk_mul_f32 v[60:61], v[60:61], v[172:173] op_sel:[0,1]
	v_pk_mul_f32 v[58:59], v[58:59], v[172:173] op_sel:[0,1]
	v_pk_mul_f32 v[64:65], v[64:65], v[174:175] op_sel_hi:[1,0]
	v_pk_mul_f32 v[62:63], v[62:63], v[174:175] op_sel_hi:[1,0]
	v_pk_mul_f32 v[68:69], v[68:69], v[174:175] op_sel:[0,1]
	v_pk_mul_f32 v[66:67], v[66:67], v[174:175] op_sel:[0,1]

; __device__ __forceinline__ float bf_lo(unsigned w) { return __uint_as_float(w << 16); }
; __device__ __forceinline__ float bf_hi(unsigned w) { return __uint_as_float(w & 0xffff0000u); }
; __device__ __forceinline__ int tid_fresh() { int t = threadIdx.x; asm volatile("" : "+v"(t)); return t; }
; __device__ __forceinline__ size_t sfrag(int r, int k) { return ((size_t)(((k >> 5) * 8 + (r >> 4)) * 64 + ((k >> 3) & 3) * 16 + (r & 15))) * 8 + (k & 7); }
; __device__ __forceinline__ void sk_final_task(int task, const float* part, bf16_t* XB, float* ssq) {
;     const int tid = tid_fresh(), wid = tid >> 6, lane = tid & 63, fr = lane & 15, fq = lane >> 4;
;     const int c0 = task * 64, rloc = 16 * wid + fr, row = MP + rloc;
;     float sq = 0.f;
; #pragma unroll
;     for (int cb = 0; cb < 4; ++cb) { bf16_t* xp = XB + (size_t)MP * D + sfrag(rloc, c0 + 16 * cb + 4 * fq); const u32x2 xo = *(const u32x2*)xp; f32x4 v = (f32x4){bf_lo(xo.x), bf_hi(xo.x), bf_lo(xo.y), bf_hi(xo.y)};
; #pragma unroll
;         for (int sp = 0; sp < 8; ++sp) v += *(const f32x4*)(part + ((size_t)sp * MS + rloc) * D + c0 + 16 * cb + 4 * fq);
;         sq += (v[0] * v[0] + v[1] * v[1]) + (v[2] * v[2] + v[3] * v[3]);
;         *(unsigned long long*)xp = pack4_act<0>(v); }
.LBB0_2086:
	v_mov_b32_e32 v10, v0
	s_waitcnt lgkmcnt(0)
	v_mov_b32_e32 v7, v2
	v_ashrrev_i32_e32 v4, 2, v10
	v_lshrrev_b32_e32 v11, 1, v10
	v_add_u32_e32 v25, s12, v10
	v_and_b32_e32 v24, 15, v10
	v_bfe_u32 v3, v10, 4, 2
	v_bfi_b32 v4, -16, v4, v10
	v_and_b32_e32 v10, 0xffffffc0, v25
	v_and_b32_e32 v26, 16, v11
	v_and_b32_e32 v6, 8, v11
	v_or3_b32 v32, v24, v10, v26
	v_lshl_add_u64 v[22:23], s[72:73], 0, v[6:7]
	v_ashrrev_i32_e32 v33, 31, v32
	v_lshl_add_u64 v[34:35], v[32:33], 4, v[22:23]
	s_ashr_i32 s9, s8, 31
	s_lshl_b64 s[10:11], s[8:9], 2
	s_add_u32 s10, s97, s10
	v_readlane_b32 s9, v253, 9
	v_ashrrev_i32_e32 v5, 31, v4
	s_addc_u32 s11, s9, s11
	v_lshlrev_b32_e32 v6, 4, v3
	v_lshl_add_u64 v[6:7], s[10:11], 0, v[6:7]
	v_lshlrev_b64 v[8:9], 13, v[4:5]
	v_lshl_add_u64 v[6:7], v[6:7], 0, v[8:9]
	v_add_u32_e32 v25, 0x200, v25
	v_and_b32_e32 v25, 0xffffffc0, v25
	v_or3_b32 v24, v24, v25, v26
	v_ashrrev_i32_e32 v25, 31, v24
	v_or_b32_e32 v28, 32, v32
	v_ashrrev_i32_e32 v29, 31, v28
	v_lshl_add_u64 v[36:37], v[28:29], 4, v[22:23]
	v_lshl_add_u64 v[38:39], v[24:25], 4, v[22:23]
	v_or_b32_e32 v28, 32, v24
	v_ashrrev_i32_e32 v29, 31, v28
	v_lshl_add_u64 v[108:109], v[28:29], 4, v[22:23]
	s_mov_b32 s11, 0
	s_mov_b32 s10, 0x100000
	v_lshl_add_u64 v[110:111], v[6:7], 0, s[10:11]
	s_mov_b32 s10, 0x200000
	v_lshl_add_u64 v[112:113], v[6:7], 0, s[10:11]
	s_mov_b32 s10, 0x300000
	v_lshl_add_u64 v[114:115], v[6:7], 0, s[10:11]
	s_mov_b32 s10, 0x400000
	v_lshl_add_u64 v[116:117], v[6:7], 0, s[10:11]
	s_mov_b32 s10, 0x500000
	v_lshl_add_u64 v[118:119], v[6:7], 0, s[10:11]
	s_mov_b32 s10, 0x600000
	v_lshl_add_u64 v[120:121], v[6:7], 0, s[10:11]
	s_mov_b32 s10, 0x700000
	v_lshl_add_u64 v[122:123], v[6:7], 0, s[10:11]
	global_load_dwordx2 v[104:105], v[34:35], off
	global_load_dwordx2 v[106:107], v[36:37], off
	global_load_dwordx4 v[40:43], v[6:7], off
	global_load_dwordx4 v[44:47], v[110:111], off
	global_load_dwordx4 v[48:51], v[112:113], off
	global_load_dwordx4 v[52:55], v[114:115], off
	global_load_dwordx4 v[56:59], v[116:117], off
	global_load_dwordx4 v[60:63], v[118:119], off
	global_load_dwordx4 v[64:67], v[120:121], off
	global_load_dwordx4 v[68:71], v[122:123], off
	global_load_dwordx4 v[72:75], v[6:7], off offset:64
	global_load_dwordx4 v[76:79], v[110:111], off offset:64
	global_load_dwordx4 v[80:83], v[112:113], off offset:64
	global_load_dwordx4 v[84:87], v[114:115], off offset:64
	global_load_dwordx4 v[88:91], v[116:117], off offset:64
	global_load_dwordx4 v[92:95], v[118:119], off offset:64
	global_load_dwordx4 v[96:99], v[120:121], off offset:64
	global_load_dwordx4 v[100:103], v[122:123], off offset:64
	s_waitcnt vmcnt(0)
	v_lshlrev_b32_e32 v12, 16, v104
	v_and_b32_e32 v13, 0xffff0000, v104
	v_lshlrev_b32_e32 v14, 16, v105
	v_and_b32_e32 v15, 0xffff0000, v105
	v_pk_add_f32 v[16:17], v[40:41], v[12:13]
	v_pk_add_f32 v[18:19], v[42:43], v[14:15]
	v_pk_add_f32 v[16:17], v[44:45], v[16:17]
	v_pk_add_f32 v[18:19], v[46:47], v[18:19]
	v_pk_add_f32 v[16:17], v[48:49], v[16:17]
	v_pk_add_f32 v[18:19], v[50:51], v[18:19]
	v_pk_add_f32 v[16:17], v[52:53], v[16:17]
	v_pk_add_f32 v[18:19], v[54:55], v[18:19]
	v_pk_add_f32 v[16:17], v[56:57], v[16:17]
	v_pk_add_f32 v[18:19], v[58:59], v[18:19]
	v_pk_add_f32 v[16:17], v[60:61], v[16:17]
	v_pk_add_f32 v[18:19], v[62:63], v[18:19]
	v_pk_add_f32 v[16:17], v[64:65], v[16:17]
	v_pk_add_f32 v[18:19], v[66:67], v[18:19]
	v_pk_add_f32 v[16:17], v[68:69], v[16:17]
	v_pk_add_f32 v[18:19], v[70:71], v[18:19]
	v_mul_f32_e32 v124, v17, v17
	v_fmac_f32_e32 v124, v16, v16
	v_mul_f32_e32 v125, v19, v19
	v_fmac_f32_e32 v125, v18, v18
	v_cvt_pk_bf16_f32 v20, v16, v17
	v_cvt_pk_bf16_f32 v21, v18, v19
	global_store_dwordx2 v[34:35], v[20:21], off
	v_add_f32_e32 v126, v124, v125
	v_lshlrev_b32_e32 v12, 16, v106
	v_and_b32_e32 v13, 0xffff0000, v106
	v_lshlrev_b32_e32 v14, 16, v107
	v_and_b32_e32 v15, 0xffff0000, v107
	v_pk_add_f32 v[16:17], v[72:73], v[12:13]
	v_pk_add_f32 v[18:19], v[74:75], v[14:15]
	v_pk_add_f32 v[16:17], v[76:77], v[16:17]
	v_pk_add_f32 v[18:19], v[78:79], v[18:19]
	v_pk_add_f32 v[16:17], v[80:81], v[16:17]
	v_pk_add_f32 v[18:19], v[82:83], v[18:19]
	v_pk_add_f32 v[16:17], v[84:85], v[16:17]
	v_pk_add_f32 v[18:19], v[86:87], v[18:19]
	v_pk_add_f32 v[16:17], v[88:89], v[16:17]
	v_pk_add_f32 v[18:19], v[90:91], v[18:19]
	v_pk_add_f32 v[16:17], v[92:93], v[16:17]
	v_pk_add_f32 v[18:19], v[94:95], v[18:19]
	v_pk_add_f32 v[16:17], v[96:97], v[16:17]
	v_pk_add_f32 v[18:19], v[98:99], v[18:19]
	v_pk_add_f32 v[16:17], v[100:101], v[16:17]
	v_pk_add_f32 v[18:19], v[102:103], v[18:19]
	v_mul_f32_e32 v124, v17, v17
	v_fmac_f32_e32 v124, v16, v16
	v_mul_f32_e32 v125, v19, v19
	v_fmac_f32_e32 v125, v18, v18
	v_cvt_pk_bf16_f32 v128, v16, v17
	v_cvt_pk_bf16_f32 v129, v18, v19
	global_store_dwordx2 v[36:37], v[128:129], off
	v_add_f32_e32 v124, v124, v125
	v_add_f32_e32 v126, v126, v124
	global_load_dwordx2 v[104:105], v[38:39], off
	global_load_dwordx2 v[106:107], v[108:109], off
	global_load_dwordx4 v[40:43], v[6:7], off offset:128
	global_load_dwordx4 v[44:47], v[110:111], off offset:128
	global_load_dwordx4 v[48:51], v[112:113], off offset:128
	global_load_dwordx4 v[52:55], v[114:115], off offset:128
	global_load_dwordx4 v[56:59], v[116:117], off offset:128
	global_load_dwordx4 v[60:63], v[118:119], off offset:128
	global_load_dwordx4 v[64:67], v[120:121], off offset:128
	global_load_dwordx4 v[68:71], v[122:123], off offset:128
	global_load_dwordx4 v[72:75], v[6:7], off offset:192
	global_load_dwordx4 v[76:79], v[110:111], off offset:192
	global_load_dwordx4 v[80:83], v[112:113], off offset:192
	global_load_dwordx4 v[84:87], v[114:115], off offset:192
	global_load_dwordx4 v[88:91], v[116:117], off offset:192
	global_load_dwordx4 v[92:95], v[118:119], off offset:192
	global_load_dwordx4 v[96:99], v[120:121], off offset:192
	global_load_dwordx4 v[100:103], v[122:123], off offset:192
	s_waitcnt vmcnt(0)
; __device__ __forceinline__ float bf_lo(unsigned w) { return __uint_as_float(w << 16); }
; __device__ __forceinline__ float bf_hi(unsigned w) { return __uint_as_float(w & 0xffff0000u); }
; __device__ __forceinline__ size_t sfrag(int r, int k) { return ((size_t)(((k >> 5) * 8 + (r >> 4)) * 64 + ((k >> 3) & 3) * 16 + (r & 15))) * 8 + (k & 7); }
; __device__ __forceinline__ void sk_final_task(int task, const float* part, bf16_t* XB, float* ssq) {
;     ...
; #pragma unroll
;     for (int cb = 0; cb < 4; ++cb) { bf16_t* xp = XB + (size_t)MP * D + sfrag(rloc, c0 + 16 * cb + 4 * fq); const u32x2 xo = *(const u32x2*)xp; f32x4 v = (f32x4){bf_lo(xo.x), bf_hi(xo.x), bf_lo(xo.y), bf_hi(xo.y)};
; #pragma unroll
;         for (int sp = 0; sp < 8; ++sp) v += *(const f32x4*)(part + ((size_t)sp * MS + rloc) * D + c0 + 16 * cb + 4 * fq);
;         sq += (v[0] * v[0] + v[1] * v[1]) + (v[2] * v[2] + v[3] * v[3]);
;         *(unsigned long long*)xp = pack4_act<0>(v); }
;     sq += __shfl_xor(sq, 16); sq += __shfl_xor(sq, 32);
;     if (fq == 0) ssq[(size_t)row * 32 + task] = sq;
	v_lshlrev_b32_e32 v12, 16, v104
	v_and_b32_e32 v13, 0xffff0000, v104
	v_lshlrev_b32_e32 v14, 16, v105
	v_and_b32_e32 v15, 0xffff0000, v105
	v_pk_add_f32 v[16:17], v[40:41], v[12:13]
	v_pk_add_f32 v[18:19], v[42:43], v[14:15]
	v_pk_add_f32 v[16:17], v[44:45], v[16:17]
	v_pk_add_f32 v[18:19], v[46:47], v[18:19]
	v_pk_add_f32 v[16:17], v[48:49], v[16:17]
	v_pk_add_f32 v[18:19], v[50:51], v[18:19]
	v_pk_add_f32 v[16:17], v[52:53], v[16:17]
	v_pk_add_f32 v[18:19], v[54:55], v[18:19]
	v_pk_add_f32 v[16:17], v[56:57], v[16:17]
	v_pk_add_f32 v[18:19], v[58:59], v[18:19]
	v_pk_add_f32 v[16:17], v[60:61], v[16:17]
	v_pk_add_f32 v[18:19], v[62:63], v[18:19]
	v_pk_add_f32 v[16:17], v[64:65], v[16:17]
	v_pk_add_f32 v[18:19], v[66:67], v[18:19]
	v_pk_add_f32 v[16:17], v[68:69], v[16:17]
	v_pk_add_f32 v[18:19], v[70:71], v[18:19]
	v_mul_f32_e32 v124, v17, v17
	v_fmac_f32_e32 v124, v16, v16
	v_mul_f32_e32 v125, v19, v19
	v_fmac_f32_e32 v125, v18, v18
	v_cvt_pk_bf16_f32 v20, v16, v17
	v_cvt_pk_bf16_f32 v21, v18, v19
	global_store_dwordx2 v[38:39], v[20:21], off
	v_add_f32_e32 v124, v124, v125
	v_add_f32_e32 v126, v126, v124
	v_lshlrev_b32_e32 v12, 16, v106
	v_and_b32_e32 v13, 0xffff0000, v106
	v_lshlrev_b32_e32 v14, 16, v107
	v_and_b32_e32 v15, 0xffff0000, v107
	v_pk_add_f32 v[16:17], v[72:73], v[12:13]
	v_pk_add_f32 v[18:19], v[74:75], v[14:15]
	v_pk_add_f32 v[16:17], v[76:77], v[16:17]
	v_pk_add_f32 v[18:19], v[78:79], v[18:19]
	v_pk_add_f32 v[16:17], v[80:81], v[16:17]
	v_pk_add_f32 v[18:19], v[82:83], v[18:19]
	v_pk_add_f32 v[16:17], v[84:85], v[16:17]
	v_pk_add_f32 v[18:19], v[86:87], v[18:19]
	v_pk_add_f32 v[16:17], v[88:89], v[16:17]
	v_pk_add_f32 v[18:19], v[90:91], v[18:19]
	v_pk_add_f32 v[16:17], v[92:93], v[16:17]
	v_pk_add_f32 v[18:19], v[94:95], v[18:19]
	v_pk_add_f32 v[16:17], v[96:97], v[16:17]
	v_pk_add_f32 v[18:19], v[98:99], v[18:19]
	v_pk_add_f32 v[16:17], v[100:101], v[16:17]
	v_pk_add_f32 v[18:19], v[102:103], v[18:19]
	v_mul_f32_e32 v124, v17, v17
	v_fmac_f32_e32 v124, v16, v16
	v_mul_f32_e32 v125, v19, v19
	v_fmac_f32_e32 v125, v18, v18
	v_cvt_pk_bf16_f32 v128, v16, v17
	v_cvt_pk_bf16_f32 v129, v18, v19
	global_store_dwordx2 v[108:109], v[128:129], off
	v_and_b32_e32 v7, 64, v196
	v_xor_b32_e32 v6, 16, v196
	v_add_f32_e32 v124, v124, v125
	v_add_u32_e32 v7, 64, v7
	v_cmp_lt_i32_e32 vcc, v6, v7
	v_add_f32_e32 v10, v126, v124
	s_nop 0
	v_cndmask_b32_e32 v6, v196, v6, vcc
	v_lshlrev_b32_e32 v6, 2, v6
	ds_bpermute_b32 v6, v6, v10
	v_xor_b32_e32 v8, 32, v196
	v_cmp_lt_i32_e32 vcc, v8, v7
	s_waitcnt lgkmcnt(0)
	v_add_f32_e32 v6, v10, v6
	v_cndmask_b32_e32 v7, v196, v8, vcc
	v_lshlrev_b32_e32 v7, 2, v7
	ds_bpermute_b32 v7, v7, v6
	v_cmp_eq_u32_e32 vcc, 0, v3
	s_and_saveexec_b64 s[10:11], vcc
	s_cbranch_execz .LBB0_2085
	v_lshlrev_b64 v[4:5], 7, v[4:5]
	v_lshl_add_u64 v[4:5], s[6:7], 0, v[4:5]
	v_add_co_u32_e32 v4, vcc, 0x100000, v4
	s_waitcnt lgkmcnt(0)
	v_add_f32_e32 v3, v6, v7
	v_addc_co_u32_e32 v5, vcc, 0, v5, vcc
	global_store_dword v[4:5], v3, off
	s_branch .LBB0_2085
